# norm phases: every load of a row (x, split-K slabs, gate, gains, scale, shift) issued together at the top of the row (was 8 dependent memory round trips per row)
# speedup vs baseline: 1.0016x; 1.0016x over previous
.LBB0_333:
	global_load_dwordx4 v[12:15], v1, s[16:17]
	global_load_dwordx4 v[16:19], v1, s[16:17] offset:1024
	global_load_dwordx4 v[20:23], v1, s[16:17] offset:2048
	global_load_dwordx4 v[24:27], v1, s[16:17] offset:3072
	s_lshr_b32 s2, s2, 10
	s_mulk_i32 s2, 0x1800
	s_addk_i32 s2, 0x1800
	s_and_b64 s[14:15], s[14:15], exec
	s_cselect_b32 s2, 0, s2
	s_lshl_b64 s[14:15], s[2:3], 2
	v_lshl_add_u64 v[40:41], v[4:5], 0, s[14:15]
	global_load_dwordx4 v[28:31], v[40:41], off
	global_load_dwordx4 v[32:35], v[2:3], off
	v_lshl_add_u64 v[42:43], v[6:7], 0, s[14:15]
	global_load_dwordx4 v[36:39], v[42:43], off
	s_lshl_b64 s[12:13], s[12:13], 11
	s_add_u32 s4, s4, s6
	s_addc_u32 s5, s5, s7
	s_add_u32 s8, s8, s10
	s_addc_u32 s9, s9, s11
	s_cmpk_lt_i32 s4, 0x1800
	global_load_dwordx4 v[60:63], v[2:3], off offset:1024
	global_load_dwordx4 v[64:67], v[40:41], off offset:1024
	global_load_dwordx4 v[68:71], v[42:43], off offset:1024
	global_load_dwordx4 v[72:75], v[2:3], off offset:2048
	global_load_dwordx4 v[76:79], v[40:41], off offset:2048
	global_load_dwordx4 v[80:83], v[42:43], off offset:2048
	global_load_dwordx4 v[84:87], v[2:3], off offset:3072
	global_load_dwordx4 v[88:91], v[40:41], off offset:3072
	global_load_dwordx4 v[92:95], v[42:43], off offset:3072
	s_nop 0
	s_waitcnt vmcnt(15)
	v_mov_b32_e32 v46, v13
	s_nop 0
	s_waitcnt vmcnt(14)
	v_mov_b32_e32 v47, v17
	v_mov_b32_e32 v44, v12
	v_mov_b32_e32 v45, v16
	s_nop 0
	s_waitcnt vmcnt(13)
	v_mov_b32_e32 v58, v21
	s_nop 0
	s_waitcnt vmcnt(12)
	v_mov_b32_e32 v59, v25
	v_pk_mul_f32 v[46:47], v[46:47], v[46:47]
	v_mov_b32_e32 v48, v14
	v_mov_b32_e32 v49, v18
	v_mov_b32_e32 v56, v20
	v_mov_b32_e32 v57, v24
	v_pk_mul_f32 v[58:59], v[58:59], v[58:59]
	v_pk_fma_f32 v[44:45], v[44:45], v[44:45], v[46:47]
	v_mov_b32_e32 v50, v15
	v_mov_b32_e32 v51, v19
	v_mov_b32_e32 v54, v22
	v_mov_b32_e32 v55, v26
	v_pk_fma_f32 v[46:47], v[56:57], v[56:57], v[58:59]
	v_pk_fma_f32 v[44:45], v[48:49], v[48:49], v[44:45]
	v_mov_b32_e32 v52, v23
	v_mov_b32_e32 v53, v27
	v_pk_fma_f32 v[46:47], v[54:55], v[54:55], v[46:47]
	v_pk_fma_f32 v[44:45], v[50:51], v[50:51], v[44:45]
	v_pk_fma_f32 v[46:47], v[52:53], v[52:53], v[46:47]
	v_add_f32_e32 v11, v44, v45
	v_add_f32_e32 v11, v11, v46
	v_add_f32_e32 v11, v11, v47
	s_nop 0
	s_waitcnt vmcnt(11)
	v_pk_add_f32 v[28:29], v[28:29], 1.0 op_sel_hi:[1,0]
	v_pk_add_f32 v[30:31], v[30:31], 1.0 op_sel_hi:[1,0]
	v_add_f32_dpp v11, v11, v11 quad_perm:[1,0,3,2] row_mask:0xf bank_mask:0xf bound_ctrl:1
	s_nop 1
	v_add_f32_dpp v11, v11, v11 quad_perm:[2,3,0,1] row_mask:0xf bank_mask:0xf bound_ctrl:1
	s_nop 1
	v_add_f32_dpp v11, v11, v11 row_half_mirror row_mask:0xf bank_mask:0xf bound_ctrl:1
	s_nop 1
	v_add_f32_dpp v11, v11, v11 row_mirror row_mask:0xf bank_mask:0xf bound_ctrl:1
	s_nop 0
	v_readlane_b32 s2, v11, 16
	v_readlane_b32 s16, v11, 48
	v_readlane_b32 s14, v11, 0
	v_readlane_b32 s15, v11, 32
	v_mov_b32_e32 v44, s2
	v_mov_b32_e32 v45, s16
	v_pk_add_f32 v[44:45], s[14:15], v[44:45]
	s_nop 0
	v_add_f32_e32 v11, v44, v45
	v_fmamk_f32 v11, v11, 0x3a800000, v10
	v_mul_f32_e32 v44, 0x4b800000, v11
	v_cmp_gt_f32_e32 vcc, s22, v11
	s_nop 1
	v_cndmask_b32_e32 v11, v11, v44, vcc
	v_rsq_f32_e32 v11, v11
	v_lshl_add_u64 v[44:45], v[8:9], 0, s[12:13]
	v_mul_f32_e32 v46, 0x45800000, v11
	v_cndmask_b32_e32 v46, v11, v46, vcc
	v_pk_mul_f32 v[12:13], v[12:13], v[46:47] op_sel_hi:[1,0]
	v_pk_mul_f32 v[14:15], v[14:15], v[46:47] op_sel_hi:[1,0]
	s_nop 0
	s_waitcnt vmcnt(10)
	v_pk_mul_f32 v[12:13], v[32:33], v[12:13]
	v_pk_mul_f32 v[14:15], v[34:35], v[14:15]
	s_nop 0
	s_waitcnt vmcnt(9)
	v_pk_fma_f32 v[12:13], v[28:29], v[12:13], v[36:37]
	v_pk_fma_f32 v[14:15], v[30:31], v[14:15], v[38:39]
	v_cvt_pk_bf16_f32 v12, v12, v13
	v_cvt_pk_bf16_f32 v13, v14, v15
	global_store_dwordx2 v[44:45], v[12:13], off
	s_nop 0
	s_nop 0
	s_nop 0
	s_nop 0
	v_pk_mul_f32 v[16:17], v[16:17], v[46:47] op_sel_hi:[1,0]
	v_pk_mul_f32 v[18:19], v[18:19], v[46:47] op_sel_hi:[1,0]
	v_pk_mul_f32 v[20:21], v[20:21], v[46:47] op_sel_hi:[1,0]
	v_pk_mul_f32 v[22:23], v[22:23], v[46:47] op_sel_hi:[1,0]
	v_pk_mul_f32 v[24:25], v[24:25], v[46:47] op_sel_hi:[1,0]
	v_pk_mul_f32 v[26:27], v[26:27], v[46:47] op_sel_hi:[1,0]
	s_nop 0
	s_waitcnt vmcnt(9)
	v_pk_mul_f32 v[12:13], v[60:61], v[16:17]
	s_nop 0
	s_waitcnt vmcnt(8)
	v_pk_add_f32 v[16:17], v[64:65], 1.0 op_sel_hi:[1,0]
	v_pk_mul_f32 v[14:15], v[62:63], v[18:19]
	v_pk_add_f32 v[18:19], v[66:67], 1.0 op_sel_hi:[1,0]
	s_nop 0
	s_waitcnt vmcnt(7)
	v_pk_fma_f32 v[12:13], v[16:17], v[12:13], v[68:69]
	v_pk_fma_f32 v[14:15], v[18:19], v[14:15], v[70:71]
	v_cvt_pk_bf16_f32 v12, v12, v13
	v_cvt_pk_bf16_f32 v13, v14, v15
	global_store_dwordx2 v[44:45], v[12:13], off offset:512
	s_nop 0
	s_nop 0
	s_nop 0
	s_nop 0
	s_nop 0
	s_waitcnt vmcnt(7)
	v_pk_mul_f32 v[12:13], v[72:73], v[20:21]
	s_nop 0
	s_waitcnt vmcnt(6)
	v_pk_add_f32 v[16:17], v[76:77], 1.0 op_sel_hi:[1,0]
	v_pk_mul_f32 v[14:15], v[74:75], v[22:23]
	v_pk_add_f32 v[18:19], v[78:79], 1.0 op_sel_hi:[1,0]
	s_nop 0
	s_waitcnt vmcnt(5)
	v_pk_fma_f32 v[12:13], v[12:13], v[16:17], v[80:81]
	v_pk_fma_f32 v[14:15], v[14:15], v[18:19], v[82:83]
	v_cvt_pk_bf16_f32 v12, v12, v13
	v_cvt_pk_bf16_f32 v13, v14, v15
	global_store_dwordx2 v[44:45], v[12:13], off offset:1024
	s_nop 0
	s_nop 0
	s_nop 0
	s_nop 0
	s_nop 0
	s_waitcnt vmcnt(5)
	v_pk_mul_f32 v[12:13], v[24:25], v[84:85]
	s_nop 0
	s_waitcnt vmcnt(4)
	v_pk_add_f32 v[16:17], v[88:89], 1.0 op_sel_hi:[1,0]
	v_pk_mul_f32 v[14:15], v[26:27], v[86:87]
	v_pk_add_f32 v[18:19], v[90:91], 1.0 op_sel_hi:[1,0]
	s_nop 0
	s_waitcnt vmcnt(3)
	v_pk_fma_f32 v[12:13], v[12:13], v[16:17], v[92:93]
	v_pk_fma_f32 v[14:15], v[14:15], v[18:19], v[94:95]
	v_cvt_pk_bf16_f32 v12, v12, v13
	v_cvt_pk_bf16_f32 v13, v14, v15
	global_store_dwordx2 v[44:45], v[12:13], off offset:1536
	s_cbranch_scc0 .LBB0_338

.LBB0_1342:
	s_lshr_b32 s2, s2, 10
	s_mulk_i32 s2, 0x1800
	s_addk_i32 s2, 0x1800
	s_and_b64 s[12:13], s[12:13], exec
	s_cselect_b32 s2, 0, s2
	s_lshl_b64 s[12:13], s[18:19], 11
	v_lshl_add_u64 v[40:41], v[8:9], 0, s[12:13]
	global_load_dwordx2 v[28:29], v[40:41], off
	v_lshl_add_u64 v[42:43], v[10:11], 0, s[12:13]
	s_lshl_b64 s[16:17], s[2:3], 2
	global_load_dwordx2 v[30:31], v[42:43], off
	global_load_dwordx4 v[2:5], v1, s[14:15]
	v_lshl_add_u64 v[44:45], v[12:13], 0, s[16:17]
	global_load_dwordx4 v[24:27], v[44:45], off
	s_lshl_b64 s[18:19], s[18:19], 12
	v_lshl_add_u64 v[46:47], v[14:15], 0, s[18:19]
	v_lshl_add_u64 v[52:53], v[16:17], 0, s[16:17]
	s_add_u32 s4, s4, s6
	s_addc_u32 s5, s5, s7
	s_add_u32 s8, s8, s10
	s_addc_u32 s9, s9, s11
	s_cmpk_lt_i32 s4, 0x1800
	v_lshl_add_u64 v[144:145], v[18:19], 0, s[16:17]
	global_load_dwordx2 v[60:61], v[40:41], off offset:512
	global_load_dwordx2 v[62:63], v[42:43], off offset:512
	global_load_dwordx4 v[64:67], v1, s[14:15] offset:1024
	global_load_dwordx4 v[68:71], v[44:45], off offset:1024
	global_load_dwordx2 v[72:73], v[40:41], off offset:1024
	global_load_dwordx2 v[74:75], v[42:43], off offset:1024
	global_load_dwordx4 v[76:79], v1, s[14:15] offset:2048
	global_load_dwordx4 v[80:83], v[44:45], off offset:2048
	global_load_dwordx2 v[84:85], v[40:41], off offset:1536
	global_load_dwordx2 v[86:87], v[42:43], off offset:1536
	global_load_dwordx4 v[88:91], v1, s[14:15] offset:3072
	global_load_dwordx4 v[92:95], v[44:45], off offset:3072
	global_load_dwordx4 v[96:99], v[6:7], off
	global_load_dwordx4 v[100:103], v[52:53], off
	global_load_dwordx4 v[104:107], v[144:145], off
	global_load_dwordx4 v[108:111], v[6:7], off offset:1024
	global_load_dwordx4 v[112:115], v[52:53], off offset:1024
	global_load_dwordx4 v[116:119], v[144:145], off offset:1024
	global_load_dwordx4 v[120:123], v[6:7], off offset:2048
	global_load_dwordx4 v[124:127], v[52:53], off offset:2048
	global_load_dwordx4 v[128:131], v[144:145], off offset:2048
	global_load_dwordx4 v[132:135], v[6:7], off offset:3072
	global_load_dwordx4 v[136:139], v[52:53], off offset:3072
	global_load_dwordx4 v[140:143], v[144:145], off offset:3072
	s_nop 0
	s_waitcnt vmcnt(27)
	v_lshlrev_b32_e32 v32, 16, v28
	v_and_b32_e32 v33, 0xffff0000, v28
	s_nop 0
	s_waitcnt vmcnt(26)
	v_lshlrev_b32_e32 v34, 16, v30
	v_and_b32_e32 v35, 0xffff0000, v30
	v_lshlrev_b32_e32 v28, 16, v29
	v_and_b32_e32 v29, 0xffff0000, v29
	v_lshlrev_b32_e32 v30, 16, v31
	v_and_b32_e32 v31, 0xffff0000, v31
	v_pk_add_f32 v[32:33], v[32:33], v[34:35]
	v_pk_add_f32 v[28:29], v[28:29], v[30:31]
	s_nop 0
	s_waitcnt vmcnt(24)
	v_pk_fma_f32 v[2:3], v[24:25], v[32:33], v[2:3]
	v_pk_fma_f32 v[4:5], v[26:27], v[28:29], v[4:5]
	global_store_dwordx4 v[46:47], v[2:5], off sc1
	s_nop 0
	s_nop 0
	s_nop 0
	s_nop 0
	v_mov_b32_e32 v54, v3
	v_mov_b32_e32 v56, v4
	v_mov_b32_e32 v58, v5
	s_nop 0
	s_waitcnt vmcnt(24)
	v_lshlrev_b32_e32 v36, 16, v60
	v_and_b32_e32 v37, 0xffff0000, v60
	s_nop 0
	s_waitcnt vmcnt(23)
	v_lshlrev_b32_e32 v38, 16, v62
	v_and_b32_e32 v39, 0xffff0000, v62
	v_lshlrev_b32_e32 v32, 16, v61
	v_and_b32_e32 v33, 0xffff0000, v61
	v_lshlrev_b32_e32 v34, 16, v63
	v_and_b32_e32 v35, 0xffff0000, v63
	v_pk_add_f32 v[36:37], v[36:37], v[38:39]
	v_pk_add_f32 v[32:33], v[32:33], v[34:35]
	s_nop 0
	s_waitcnt vmcnt(21)
	v_pk_fma_f32 v[24:25], v[68:69], v[36:37], v[64:65]
	v_pk_fma_f32 v[26:27], v[70:71], v[32:33], v[66:67]
	global_store_dwordx4 v[46:47], v[24:27], off offset:1024 sc1
	s_nop 0
	s_nop 0
	s_nop 0
	s_nop 0
	v_mov_b32_e32 v55, v25
	v_pk_mul_f32 v[54:55], v[54:55], v[54:55]
	v_mov_b32_e32 v57, v26
	v_mov_b32_e32 v59, v27
	s_nop 0
	s_waitcnt vmcnt(21)
	v_lshlrev_b32_e32 v48, 16, v72
	v_and_b32_e32 v49, 0xffff0000, v72
	s_nop 0
	s_waitcnt vmcnt(20)
	v_lshlrev_b32_e32 v50, 16, v74
	v_and_b32_e32 v51, 0xffff0000, v74
	v_lshlrev_b32_e32 v36, 16, v73
	v_and_b32_e32 v37, 0xffff0000, v73
	v_lshlrev_b32_e32 v38, 16, v75
	v_and_b32_e32 v39, 0xffff0000, v75
	v_pk_add_f32 v[48:49], v[48:49], v[50:51]
	v_pk_add_f32 v[36:37], v[36:37], v[38:39]
	s_nop 0
	s_waitcnt vmcnt(18)
	v_pk_fma_f32 v[28:29], v[80:81], v[48:49], v[76:77]
	v_pk_fma_f32 v[30:31], v[82:83], v[36:37], v[78:79]
	global_store_dwordx4 v[46:47], v[28:31], off offset:2048 sc1
	s_nop 0
	s_nop 0
	s_nop 0
	s_nop 0
	s_nop 0
	s_waitcnt vmcnt(18)
	v_lshlrev_b32_e32 v40, 16, v84
	v_and_b32_e32 v41, 0xffff0000, v84
	s_nop 0
	s_waitcnt vmcnt(17)
	v_lshlrev_b32_e32 v42, 16, v86
	v_and_b32_e32 v43, 0xffff0000, v86
	v_lshlrev_b32_e32 v44, 16, v85
	v_and_b32_e32 v45, 0xffff0000, v85
	v_lshlrev_b32_e32 v48, 16, v87
	v_and_b32_e32 v49, 0xffff0000, v87
	v_pk_add_f32 v[40:41], v[40:41], v[42:43]
	v_pk_add_f32 v[42:43], v[44:45], v[48:49]
	s_nop 0
	s_waitcnt vmcnt(15)
	v_pk_fma_f32 v[32:33], v[92:93], v[40:41], v[88:89]
	v_pk_fma_f32 v[34:35], v[94:95], v[42:43], v[90:91]
	global_store_dwordx4 v[46:47], v[32:35], off offset:3072 sc1
	s_nop 0
	s_nop 0
	v_lshl_add_u64 v[48:49], v[18:19], 0, s[16:17]
	s_nop 0
	v_mov_b32_e32 v50, v2
	v_mov_b32_e32 v51, v24
	v_pk_fma_f32 v[50:51], v[50:51], v[50:51], v[54:55]
	v_mov_b32_e32 v54, v30
	v_pk_fma_f32 v[50:51], v[56:57], v[56:57], v[50:51]
	v_mov_b32_e32 v56, v28
	v_pk_fma_f32 v[50:51], v[58:59], v[58:59], v[50:51]
	v_mov_b32_e32 v58, v29
	v_mov_b32_e32 v59, v33
	v_mov_b32_e32 v57, v32
	v_pk_mul_f32 v[58:59], v[58:59], v[58:59]
	v_mov_b32_e32 v55, v34
	v_pk_fma_f32 v[56:57], v[56:57], v[56:57], v[58:59]
	v_add_f32_e32 v23, v50, v51
	v_mov_b32_e32 v50, v31
	v_mov_b32_e32 v51, v35
	v_pk_fma_f32 v[54:55], v[54:55], v[54:55], v[56:57]
	s_nop 0
	v_pk_fma_f32 v[50:51], v[50:51], v[50:51], v[54:55]
	s_nop 0
	v_add_f32_e32 v23, v23, v50
	v_add_f32_e32 v23, v23, v51
	s_nop 1
	v_add_f32_dpp v23, v23, v23 quad_perm:[1,0,3,2] row_mask:0xf bank_mask:0xf bound_ctrl:1
	s_nop 1
	v_add_f32_dpp v23, v23, v23 quad_perm:[2,3,0,1] row_mask:0xf bank_mask:0xf bound_ctrl:1
	s_nop 1
	v_add_f32_dpp v23, v23, v23 row_half_mirror row_mask:0xf bank_mask:0xf bound_ctrl:1
	s_nop 1
	v_add_f32_dpp v23, v23, v23 row_mirror row_mask:0xf bank_mask:0xf bound_ctrl:1
	s_nop 0
	v_readlane_b32 s2, v23, 16
	v_readlane_b32 s16, v23, 48
	v_readlane_b32 s14, v23, 0
	v_readlane_b32 s15, v23, 32
	v_mov_b32_e32 v50, s2
	v_mov_b32_e32 v51, s16
	v_pk_add_f32 v[50:51], s[14:15], v[50:51]
	s_nop 0
	v_add_f32_e32 v23, v50, v51
	v_fmamk_f32 v23, v23, 0x3a800000, v22
	v_mul_f32_e32 v50, 0x4b800000, v23
	v_cmp_gt_f32_e32 vcc, s22, v23
	s_nop 1
	v_cndmask_b32_e32 v23, v23, v50, vcc
	v_rsq_f32_e32 v23, v23
	v_lshl_add_u64 v[50:51], v[20:21], 0, s[12:13]
	v_mul_f32_e32 v54, 0x45800000, v23
	v_cndmask_b32_e32 v54, v23, v54, vcc
	v_pk_mul_f32 v[2:3], v[2:3], v[54:55] op_sel_hi:[1,0]
	v_pk_mul_f32 v[4:5], v[4:5], v[54:55] op_sel_hi:[1,0]
	v_pk_mul_f32 v[24:25], v[24:25], v[54:55] op_sel_hi:[1,0]
	v_pk_mul_f32 v[26:27], v[26:27], v[54:55] op_sel_hi:[1,0]
	v_pk_mul_f32 v[28:29], v[28:29], v[54:55] op_sel_hi:[1,0]
	v_pk_mul_f32 v[30:31], v[30:31], v[54:55] op_sel_hi:[1,0]
	v_pk_mul_f32 v[32:33], v[32:33], v[54:55] op_sel_hi:[1,0]
	v_pk_mul_f32 v[34:35], v[34:35], v[54:55] op_sel_hi:[1,0]
	s_nop 0
	s_waitcnt vmcnt(15)
	v_pk_mul_f32 v[2:3], v[96:97], v[2:3]
	s_nop 0
	s_waitcnt vmcnt(14)
	v_pk_add_f32 v[36:37], v[100:101], 1.0 op_sel_hi:[1,0]
	v_pk_mul_f32 v[4:5], v[98:99], v[4:5]
	v_pk_add_f32 v[38:39], v[102:103], 1.0 op_sel_hi:[1,0]
	s_nop 0
	s_waitcnt vmcnt(13)
	v_pk_fma_f32 v[2:3], v[36:37], v[2:3], v[104:105]
	v_pk_fma_f32 v[4:5], v[38:39], v[4:5], v[106:107]
	v_cvt_pk_bf16_f32 v2, v2, v3
	v_cvt_pk_bf16_f32 v3, v4, v5
	global_store_dwordx2 v[50:51], v[2:3], off
	s_nop 0
	s_nop 0
	s_nop 0
	s_nop 0
	s_nop 0
	s_waitcnt vmcnt(13)
	v_pk_mul_f32 v[2:3], v[108:109], v[24:25]
	s_nop 0
	s_waitcnt vmcnt(12)
	v_pk_add_f32 v[24:25], v[112:113], 1.0 op_sel_hi:[1,0]
	v_pk_mul_f32 v[4:5], v[110:111], v[26:27]
	v_pk_add_f32 v[26:27], v[114:115], 1.0 op_sel_hi:[1,0]
	s_nop 0
	s_waitcnt vmcnt(11)
	v_pk_fma_f32 v[2:3], v[24:25], v[2:3], v[116:117]
	v_pk_fma_f32 v[4:5], v[26:27], v[4:5], v[118:119]
	v_cvt_pk_bf16_f32 v2, v2, v3
	v_cvt_pk_bf16_f32 v3, v4, v5
	global_store_dwordx2 v[50:51], v[2:3], off offset:512
	s_nop 0
	s_nop 0
	s_nop 0
	s_nop 0
	s_nop 0
	s_waitcnt vmcnt(11)
	v_pk_mul_f32 v[2:3], v[120:121], v[28:29]
	s_nop 0
	s_waitcnt vmcnt(10)
	v_pk_add_f32 v[24:25], v[124:125], 1.0 op_sel_hi:[1,0]
	v_pk_mul_f32 v[4:5], v[122:123], v[30:31]
	v_pk_add_f32 v[26:27], v[126:127], 1.0 op_sel_hi:[1,0]
	s_nop 0
	s_waitcnt vmcnt(9)
	v_pk_fma_f32 v[2:3], v[2:3], v[24:25], v[128:129]
	v_pk_fma_f32 v[4:5], v[4:5], v[26:27], v[130:131]
	v_cvt_pk_bf16_f32 v2, v2, v3
	v_cvt_pk_bf16_f32 v3, v4, v5
	global_store_dwordx2 v[50:51], v[2:3], off offset:1024
	s_nop 0
	s_nop 0
	s_nop 0
	s_nop 0
	s_nop 0
	s_waitcnt vmcnt(9)
	v_pk_mul_f32 v[2:3], v[32:33], v[132:133]
	s_nop 0
	s_waitcnt vmcnt(8)
	v_pk_add_f32 v[24:25], v[136:137], 1.0 op_sel_hi:[1,0]
	v_pk_mul_f32 v[4:5], v[34:35], v[134:135]
	v_pk_add_f32 v[26:27], v[138:139], 1.0 op_sel_hi:[1,0]
	s_nop 0
	s_waitcnt vmcnt(7)
	v_pk_fma_f32 v[2:3], v[2:3], v[24:25], v[140:141]
	v_pk_fma_f32 v[4:5], v[4:5], v[26:27], v[142:143]
	v_cvt_pk_bf16_f32 v2, v2, v3
	v_cvt_pk_bf16_f32 v3, v4, v5
	global_store_dwordx2 v[50:51], v[2:3], off offset:1536
	s_cbranch_scc0 .LBB0_1347

.LBB0_2457:
	s_lshr_b32 s2, s2, 10
	s_mulk_i32 s2, 0x1800
	s_addk_i32 s2, 0x1800
	s_and_b64 s[12:13], s[12:13], exec
	s_cselect_b32 s2, 0, s2
	s_lshl_b64 s[12:13], s[18:19], 11
	v_lshl_add_u64 v[46:47], v[14:15], 0, s[12:13]
	global_load_dwordx2 v[34:35], v[46:47], off
	v_lshl_add_u64 v[48:49], v[16:17], 0, s[12:13]
	s_lshl_b64 s[14:15], s[2:3], 2
	global_load_dwordx2 v[36:37], v[48:49], off
	global_load_dwordx4 v[2:5], v1, s[16:17]
	v_lshl_add_u64 v[50:51], v[18:19], 0, s[14:15]
	global_load_dwordx4 v[30:33], v[50:51], off
	s_lshl_b64 s[18:19], s[18:19], 12
	v_lshl_add_u64 v[52:53], v[20:21], 0, s[18:19]
	v_lshl_add_u64 v[58:59], v[22:23], 0, s[14:15]
	s_add_u32 s4, s4, s6
	s_addc_u32 s5, s5, s7
	s_add_u32 s8, s8, s10
	s_addc_u32 s9, s9, s11
	s_cmpk_lt_i32 s4, 0x1800
	v_lshl_add_u64 v[154:155], v[24:25], 0, s[14:15]
	global_load_dwordx2 v[70:71], v[46:47], off offset:512
	global_load_dwordx2 v[72:73], v[48:49], off offset:512
	global_load_dwordx4 v[74:77], v1, s[16:17] offset:1024
	global_load_dwordx4 v[78:81], v[50:51], off offset:1024
	global_load_dwordx2 v[82:83], v[46:47], off offset:1024
	global_load_dwordx2 v[84:85], v[48:49], off offset:1024
	global_load_dwordx4 v[86:89], v1, s[16:17] offset:2048
	global_load_dwordx4 v[90:93], v[50:51], off offset:2048
	global_load_dwordx2 v[94:95], v[46:47], off offset:1536
	global_load_dwordx2 v[96:97], v[48:49], off offset:1536
	global_load_dwordx4 v[98:101], v1, s[16:17] offset:3072
	global_load_dwordx4 v[102:105], v[50:51], off offset:3072
	global_load_dwordx4 v[106:109], v[6:7], off
	global_load_dwordx4 v[110:113], v[58:59], off
	global_load_dwordx4 v[114:117], v[154:155], off
	global_load_dwordx4 v[118:121], v[8:9], off
	global_load_dwordx4 v[122:125], v[58:59], off offset:1024
	global_load_dwordx4 v[126:129], v[154:155], off offset:1024
	global_load_dwordx4 v[130:133], v[10:11], off
	global_load_dwordx4 v[134:137], v[58:59], off offset:2048
	global_load_dwordx4 v[138:141], v[154:155], off offset:2048
	global_load_dwordx4 v[142:145], v[12:13], off
	global_load_dwordx4 v[146:149], v[58:59], off offset:3072
	global_load_dwordx4 v[150:153], v[154:155], off offset:3072
	s_nop 0
	s_waitcnt vmcnt(27)
	v_lshlrev_b32_e32 v38, 16, v34
	v_and_b32_e32 v39, 0xffff0000, v34
	s_nop 0
	s_waitcnt vmcnt(26)
	v_lshlrev_b32_e32 v40, 16, v36
	v_and_b32_e32 v41, 0xffff0000, v36
	v_lshlrev_b32_e32 v34, 16, v35
	v_and_b32_e32 v35, 0xffff0000, v35
	v_lshlrev_b32_e32 v36, 16, v37
	v_and_b32_e32 v37, 0xffff0000, v37
	v_pk_add_f32 v[38:39], v[38:39], v[40:41]
	v_pk_add_f32 v[34:35], v[34:35], v[36:37]
	s_nop 0
	s_waitcnt vmcnt(24)
	v_pk_fma_f32 v[2:3], v[30:31], v[38:39], v[2:3]
	v_pk_fma_f32 v[4:5], v[32:33], v[34:35], v[4:5]
	global_store_dwordx4 v[52:53], v[2:5], off sc1
	s_nop 0
	s_nop 0
	s_nop 0
	s_nop 0
	v_mov_b32_e32 v60, v3
	v_mov_b32_e32 v62, v4
	v_mov_b32_e32 v64, v5
	s_nop 0
	s_waitcnt vmcnt(24)
	v_lshlrev_b32_e32 v42, 16, v70
	v_and_b32_e32 v43, 0xffff0000, v70
	s_nop 0
	s_waitcnt vmcnt(23)
	v_lshlrev_b32_e32 v44, 16, v72
	v_and_b32_e32 v45, 0xffff0000, v72
	v_lshlrev_b32_e32 v38, 16, v71
	v_and_b32_e32 v39, 0xffff0000, v71
	v_lshlrev_b32_e32 v40, 16, v73
	v_and_b32_e32 v41, 0xffff0000, v73
	v_pk_add_f32 v[42:43], v[42:43], v[44:45]
	v_pk_add_f32 v[38:39], v[38:39], v[40:41]
	s_nop 0
	s_waitcnt vmcnt(21)
	v_pk_fma_f32 v[30:31], v[78:79], v[42:43], v[74:75]
	v_pk_fma_f32 v[32:33], v[80:81], v[38:39], v[76:77]
	global_store_dwordx4 v[52:53], v[30:33], off offset:1024 sc1
	s_nop 0
	s_nop 0
	s_nop 0
	s_nop 0
	v_mov_b32_e32 v61, v31
	v_pk_mul_f32 v[60:61], v[60:61], v[60:61]
	v_mov_b32_e32 v63, v32
	v_mov_b32_e32 v65, v33
	s_nop 0
	s_waitcnt vmcnt(21)
	v_lshlrev_b32_e32 v54, 16, v82
	v_and_b32_e32 v55, 0xffff0000, v82
	s_nop 0
	s_waitcnt vmcnt(20)
	v_lshlrev_b32_e32 v56, 16, v84
	v_and_b32_e32 v57, 0xffff0000, v84
	v_lshlrev_b32_e32 v42, 16, v83
	v_and_b32_e32 v43, 0xffff0000, v83
	v_lshlrev_b32_e32 v44, 16, v85
	v_and_b32_e32 v45, 0xffff0000, v85
	v_pk_add_f32 v[54:55], v[54:55], v[56:57]
	v_pk_add_f32 v[42:43], v[42:43], v[44:45]
	s_nop 0
	s_waitcnt vmcnt(18)
	v_pk_fma_f32 v[34:35], v[90:91], v[54:55], v[86:87]
	v_pk_fma_f32 v[36:37], v[92:93], v[42:43], v[88:89]
	global_store_dwordx4 v[52:53], v[34:37], off offset:2048 sc1
	s_nop 0
	s_nop 0
	s_nop 0
	s_nop 0
	s_nop 0
	s_waitcnt vmcnt(18)
	v_lshlrev_b32_e32 v46, 16, v94
	v_and_b32_e32 v47, 0xffff0000, v94
	s_nop 0
	s_waitcnt vmcnt(17)
	v_lshlrev_b32_e32 v48, 16, v96
	v_and_b32_e32 v49, 0xffff0000, v96
	v_lshlrev_b32_e32 v50, 16, v95
	v_and_b32_e32 v51, 0xffff0000, v95
	v_lshlrev_b32_e32 v54, 16, v97
	v_and_b32_e32 v55, 0xffff0000, v97
	v_pk_add_f32 v[46:47], v[46:47], v[48:49]
	v_pk_add_f32 v[48:49], v[50:51], v[54:55]
	s_nop 0
	s_waitcnt vmcnt(15)
	v_pk_fma_f32 v[38:39], v[102:103], v[46:47], v[98:99]
	v_pk_fma_f32 v[40:41], v[104:105], v[48:49], v[100:101]
	global_store_dwordx4 v[52:53], v[38:41], off offset:3072 sc1
	s_nop 0
	s_nop 0
	v_lshl_add_u64 v[54:55], v[24:25], 0, s[14:15]
	s_nop 0
	v_mov_b32_e32 v56, v2
	v_mov_b32_e32 v57, v30
	v_pk_fma_f32 v[56:57], v[56:57], v[56:57], v[60:61]
	v_mov_b32_e32 v60, v36
	v_pk_fma_f32 v[56:57], v[62:63], v[62:63], v[56:57]
	v_mov_b32_e32 v62, v34
	v_pk_fma_f32 v[56:57], v[64:65], v[64:65], v[56:57]
	v_mov_b32_e32 v64, v35
	v_mov_b32_e32 v65, v39
	v_mov_b32_e32 v63, v38
	v_pk_mul_f32 v[64:65], v[64:65], v[64:65]
	v_mov_b32_e32 v61, v40
	v_pk_fma_f32 v[62:63], v[62:63], v[62:63], v[64:65]
	v_add_f32_e32 v29, v56, v57
	v_mov_b32_e32 v56, v37
	v_mov_b32_e32 v57, v41
	v_pk_fma_f32 v[60:61], v[60:61], v[60:61], v[62:63]
	s_nop 0
	v_pk_fma_f32 v[56:57], v[56:57], v[56:57], v[60:61]
	s_nop 0
	v_add_f32_e32 v29, v29, v56
	v_add_f32_e32 v29, v29, v57
	s_nop 1
	v_add_f32_dpp v29, v29, v29 quad_perm:[1,0,3,2] row_mask:0xf bank_mask:0xf bound_ctrl:1
	s_nop 1
	v_add_f32_dpp v29, v29, v29 quad_perm:[2,3,0,1] row_mask:0xf bank_mask:0xf bound_ctrl:1
	s_nop 1
	v_add_f32_dpp v29, v29, v29 row_half_mirror row_mask:0xf bank_mask:0xf bound_ctrl:1
	s_nop 1
	v_add_f32_dpp v29, v29, v29 row_mirror row_mask:0xf bank_mask:0xf bound_ctrl:1
	s_nop 0
	v_readlane_b32 s2, v29, 16
	v_readlane_b32 s16, v29, 48
	v_readlane_b32 s14, v29, 0
	v_readlane_b32 s15, v29, 32
	v_mov_b32_e32 v56, s2
	v_mov_b32_e32 v57, s16
	v_pk_add_f32 v[56:57], s[14:15], v[56:57]
	s_nop 0
	v_add_f32_e32 v29, v56, v57
	v_fmamk_f32 v29, v29, 0x3a800000, v28
	v_mul_f32_e32 v56, 0x4b800000, v29
	v_cmp_gt_f32_e32 vcc, s22, v29
	s_nop 1
	v_cndmask_b32_e32 v29, v29, v56, vcc
	v_rsq_f32_e32 v29, v29
	v_lshl_add_u64 v[56:57], v[26:27], 0, s[12:13]
	v_mul_f32_e32 v60, 0x45800000, v29
	v_cndmask_b32_e32 v60, v29, v60, vcc
	v_pk_mul_f32 v[2:3], v[2:3], v[60:61] op_sel_hi:[1,0]
	v_pk_mul_f32 v[4:5], v[4:5], v[60:61] op_sel_hi:[1,0]
	v_pk_mul_f32 v[30:31], v[30:31], v[60:61] op_sel_hi:[1,0]
	v_pk_mul_f32 v[32:33], v[32:33], v[60:61] op_sel_hi:[1,0]
	v_pk_mul_f32 v[34:35], v[34:35], v[60:61] op_sel_hi:[1,0]
	v_pk_mul_f32 v[36:37], v[36:37], v[60:61] op_sel_hi:[1,0]
	v_pk_mul_f32 v[38:39], v[38:39], v[60:61] op_sel_hi:[1,0]
	v_pk_mul_f32 v[40:41], v[40:41], v[60:61] op_sel_hi:[1,0]
	s_nop 0
	s_waitcnt vmcnt(15)
	v_pk_mul_f32 v[2:3], v[106:107], v[2:3]
	s_nop 0
	s_waitcnt vmcnt(14)
	v_pk_add_f32 v[42:43], v[110:111], 1.0 op_sel_hi:[1,0]
	v_pk_mul_f32 v[4:5], v[108:109], v[4:5]
	v_pk_add_f32 v[44:45], v[112:113], 1.0 op_sel_hi:[1,0]
	s_nop 0
	s_waitcnt vmcnt(13)
	v_pk_fma_f32 v[2:3], v[42:43], v[2:3], v[114:115]
	v_pk_fma_f32 v[4:5], v[44:45], v[4:5], v[116:117]
	v_cvt_pk_bf16_f32 v2, v2, v3
	v_cvt_pk_bf16_f32 v3, v4, v5
	global_store_dwordx2 v[56:57], v[2:3], off
	s_nop 0
	s_nop 0
	s_nop 0
	s_nop 0
	s_nop 0
	s_waitcnt vmcnt(13)
	v_pk_mul_f32 v[2:3], v[118:119], v[30:31]
	s_nop 0
	s_waitcnt vmcnt(12)
	v_pk_add_f32 v[30:31], v[122:123], 1.0 op_sel_hi:[1,0]
	v_pk_mul_f32 v[4:5], v[120:121], v[32:33]
	v_pk_add_f32 v[32:33], v[124:125], 1.0 op_sel_hi:[1,0]
	s_nop 0
	s_waitcnt vmcnt(11)
	v_pk_fma_f32 v[2:3], v[30:31], v[2:3], v[126:127]
	v_pk_fma_f32 v[4:5], v[32:33], v[4:5], v[128:129]
	v_cvt_pk_bf16_f32 v2, v2, v3
	v_cvt_pk_bf16_f32 v3, v4, v5
	global_store_dwordx2 v[56:57], v[2:3], off offset:512
	s_nop 0
	s_nop 0
	s_nop 0
	s_nop 0
	s_nop 0
	s_waitcnt vmcnt(11)
	v_pk_mul_f32 v[2:3], v[130:131], v[34:35]
	s_nop 0
	s_waitcnt vmcnt(10)
	v_pk_add_f32 v[30:31], v[134:135], 1.0 op_sel_hi:[1,0]
	v_pk_mul_f32 v[4:5], v[132:133], v[36:37]
	v_pk_add_f32 v[32:33], v[136:137], 1.0 op_sel_hi:[1,0]
	s_nop 0
	s_waitcnt vmcnt(9)
	v_pk_fma_f32 v[2:3], v[2:3], v[30:31], v[138:139]
	v_pk_fma_f32 v[4:5], v[4:5], v[32:33], v[140:141]
	v_cvt_pk_bf16_f32 v2, v2, v3
	v_cvt_pk_bf16_f32 v3, v4, v5
	global_store_dwordx2 v[56:57], v[2:3], off offset:1024
	s_nop 0
	s_nop 0
	s_nop 0
	s_nop 0
	s_nop 0
	s_waitcnt vmcnt(9)
	v_pk_mul_f32 v[2:3], v[38:39], v[142:143]
	s_nop 0
	s_waitcnt vmcnt(8)
	v_pk_add_f32 v[30:31], v[146:147], 1.0 op_sel_hi:[1,0]
	v_pk_mul_f32 v[4:5], v[40:41], v[144:145]
	v_pk_add_f32 v[32:33], v[148:149], 1.0 op_sel_hi:[1,0]
	s_nop 0
	s_waitcnt vmcnt(7)
	v_pk_fma_f32 v[2:3], v[2:3], v[30:31], v[150:151]
	v_pk_fma_f32 v[4:5], v[4:5], v[32:33], v[152:153]
	v_cvt_pk_bf16_f32 v2, v2, v3
	v_cvt_pk_bf16_f32 v3, v4, v5
	global_store_dwordx2 v[56:57], v[2:3], off offset:1536
	s_cbranch_scc0 .LBB0_2462
